# strategy 7 instruction selection: merge gate section uses packed fp32 mul/add/fma for the sigmoid steps and the gated accumulate
# speedup vs baseline: 1.0037x; 1.0037x over previous
; #define RTID opaque_tid()
; template <int MI, int NJ> ...
;     ...
;     const u16* a = ra_ + buf * AROWS * 64;
;     const u16* b = rb_ + buf * BROWS * 64;
; #pragma unroll
;     for (int ks = 0; ks < 2; ++ks) {
;       const u16* a_ = ks ? a + dsw : a;
;       const u16* b_ = ks ? b + dsw : b;
;       bf16x8 bfr[NJ];
; #pragma unroll
;       for (int j = 0; j < NJ; ++j) bfr[j] = *(const bf16x8*)(b_ + j * 16 * 64);
; #pragma unroll
;       for (int ih = 0; ih < MI / 4; ++ih) {
;         bf16x8 af[4];
; #pragma unroll
;         for (int i = 0; i < 4; ++i) af[i] = *(const bf16x8*)(a_ + (ih * 4 + i) * 16 * 64);
; #pragma unroll
;         for (int i = 0; i < 4; ++i)
; #pragma unroll
;           for (int j = 0; j < NJ; ++j) acc[ih * 4 + i][j] = mfma16(af[i], bfr[j], acc[ih * 4 + i][j]);
;       }
;     }
;     __builtin_amdgcn_s_setprio(0);
;     __builtin_amdgcn_sched_barrier(0);
;     __syncthreads();
; __device__ __forceinline__ void phase_merge(const Params& p, u16* smem, volatile LAS unsigned* vb_) {
;     ...
;       const int tid2 = RTID;
; #pragma unroll
;       for (int k = 0; k < 8; ++k) {
;         const int c = tid2 + 512 * k;
;         const int row = c >> 5, ch = c & 31;
;         *(uint4*)(smem + row * 264 + ch * 8) = *(const uint4*)(MG + (size_t)(mt * 128 + row) * 3072 + n * 1024 + nt * 256 + ch * 8);
;       }
;       __syncthreads();
.Lmg_wdone:
	v_cndmask_b32_e32 v6, v172, v178, vcc
	v_cndmask_b32_e32 v7, v173, v179, vcc
	v_cndmask_b32_e32 v11, v177, v181, vcc
	v_cndmask_b32_e32 v10, v176, v180, vcc
	v_add_co_u32_e32 v12, vcc, s77, v6
	s_mov_b32 s40, 0x90000
	s_nop 0
	v_addc_co_u32_e32 v13, vcc, 0, v7, vcc
	v_add_co_u32_e32 v14, vcc, s77, v10
	global_load_dwordx4 v[2:5], v[6:7], off
	s_nop 0
	v_addc_co_u32_e32 v15, vcc, 0, v11, vcc
	v_add_co_u32_e32 v18, vcc, s54, v10
	global_load_dwordx4 v[6:9], v[10:11], off
	s_nop 0
	v_addc_co_u32_e32 v19, vcc, 0, v11, vcc
	v_add_co_u32_e32 v22, vcc, s40, v10
	s_nop 1
	v_addc_co_u32_e32 v23, vcc, 0, v11, vcc
	global_load_dwordx4 v[10:13], v[12:13], off
	s_nop 0
	global_load_dwordx4 v[14:17], v[14:15], off
	s_nop 0
	global_load_dwordx4 v[18:21], v[18:19], off
	s_nop 0
	global_load_dwordx4 v[22:25], v[22:23], off
	s_setprio 1
	v_lshl_add_u32 v0, s13, 14, v184
	v_lshl_or_b32 v187, s13, 15, v185
	ds_read_b128 v[192:195], v187 offset:32768
	ds_read_b128 v[196:199], v187 offset:34816
	ds_read_b128 v[204:207], v187 offset:36864
	ds_read_b128 v[208:211], v187 offset:38912
	ds_read_b128 v[188:191], v0
	ds_read_b128 v[246:249], v0 offset:2048
	v_add_u32_e32 v187, v187, v186
	s_waitcnt lgkmcnt(1)
	v_mfma_f32_16x16x32_bf16 v[86:89], v[188:191], v[192:195], v[86:89]
	s_waitcnt lgkmcnt(4)
	v_mfma_f32_16x16x32_bf16 v[82:85], v[188:191], v[196:199], v[82:85]
	s_waitcnt lgkmcnt(3)
	v_mfma_f32_16x16x32_bf16 v[78:81], v[188:191], v[204:207], v[78:81]
	s_waitcnt lgkmcnt(2)
	v_mfma_f32_16x16x32_bf16 v[74:77], v[188:191], v[208:211], v[74:77]
	ds_read_b128 v[188:191], v0 offset:4096
	s_waitcnt lgkmcnt(1)
	v_mfma_f32_16x16x32_bf16 v[70:73], v[246:249], v[192:195], v[70:73]
	v_mfma_f32_16x16x32_bf16 v[66:69], v[246:249], v[196:199], v[66:69]
	v_mfma_f32_16x16x32_bf16 v[62:65], v[246:249], v[204:207], v[62:65]
	v_mfma_f32_16x16x32_bf16 v[58:61], v[246:249], v[208:211], v[58:61]
	ds_read_b128 v[246:249], v0 offset:6144
	v_add_u32_e32 v0, v0, v186
	s_waitcnt lgkmcnt(1)
	v_mfma_f32_16x16x32_bf16 v[54:57], v[188:191], v[192:195], v[54:57]
	v_mfma_f32_16x16x32_bf16 v[50:53], v[188:191], v[196:199], v[50:53]
	v_mfma_f32_16x16x32_bf16 v[46:49], v[188:191], v[204:207], v[46:49]
	v_mfma_f32_16x16x32_bf16 v[42:45], v[188:191], v[208:211], v[42:45]
	ds_read_b128 v[188:191], v0
	s_waitcnt lgkmcnt(1)
	v_mfma_f32_16x16x32_bf16 v[38:41], v[246:249], v[192:195], v[38:41]
	ds_read_b128 v[192:195], v187 offset:32768
	v_mfma_f32_16x16x32_bf16 v[34:37], v[246:249], v[196:199], v[34:37]
	ds_read_b128 v[196:199], v187 offset:34816
	v_mfma_f32_16x16x32_bf16 v[30:33], v[246:249], v[204:207], v[30:33]
	ds_read_b128 v[204:207], v187 offset:36864
	v_mfma_f32_16x16x32_bf16 v[26:29], v[246:249], v[208:211], v[26:29]
	ds_read_b128 v[208:211], v187 offset:38912
	ds_read_b128 v[246:249], v0 offset:2048
	s_waitcnt lgkmcnt(4)
	v_mfma_f32_16x16x32_bf16 v[86:89], v[188:191], v[192:195], v[86:89]
	s_waitcnt lgkmcnt(3)
	v_mfma_f32_16x16x32_bf16 v[82:85], v[188:191], v[196:199], v[82:85]
	s_waitcnt lgkmcnt(2)
	v_mfma_f32_16x16x32_bf16 v[78:81], v[188:191], v[204:207], v[78:81]
	s_waitcnt lgkmcnt(1)
	v_mfma_f32_16x16x32_bf16 v[74:77], v[188:191], v[208:211], v[74:77]
	ds_read_b128 v[188:191], v0 offset:4096
	s_waitcnt lgkmcnt(1)
	v_mfma_f32_16x16x32_bf16 v[70:73], v[246:249], v[192:195], v[70:73]
	v_mfma_f32_16x16x32_bf16 v[66:69], v[246:249], v[196:199], v[66:69]
	v_mfma_f32_16x16x32_bf16 v[62:65], v[246:249], v[204:207], v[62:65]
	v_mfma_f32_16x16x32_bf16 v[58:61], v[246:249], v[208:211], v[58:61]
	ds_read_b128 v[246:249], v0 offset:6144
	s_waitcnt lgkmcnt(1)
	v_mfma_f32_16x16x32_bf16 v[54:57], v[188:191], v[192:195], v[54:57]
	v_mfma_f32_16x16x32_bf16 v[50:53], v[188:191], v[196:199], v[50:53]
	v_mfma_f32_16x16x32_bf16 v[46:49], v[188:191], v[204:207], v[46:49]
	v_mfma_f32_16x16x32_bf16 v[42:45], v[188:191], v[208:211], v[42:45]
	s_waitcnt lgkmcnt(0)
	v_mfma_f32_16x16x32_bf16 v[38:41], v[246:249], v[192:195], v[38:41]
	v_mfma_f32_16x16x32_bf16 v[34:37], v[246:249], v[196:199], v[34:37]
	v_mfma_f32_16x16x32_bf16 v[30:33], v[246:249], v[204:207], v[30:33]
	v_mfma_f32_16x16x32_bf16 v[26:29], v[246:249], v[208:211], v[26:29]
	s_setprio 0
	s_add_i32 s12, s12, 1
	v_lshl_add_u64 v[180:181], v[180:181], 0, s[26:27]
	s_cmp_lg_u32 s12, 8
	v_lshl_add_u64 v[178:179], v[178:179], 0, s[26:27]
	s_barrier
	s_cbranch_scc1 .LBB0_26
	v_lshrrev_b32_e32 v204, 5, v175
	v_and_b32_e32 v205, 31, v175
	v_mul_u32_u24_e32 v204, 0x210, v204
	v_lshl_add_u32 v204, v205, 4, v204
	s_waitcnt vmcnt(6)
	ds_write_b128 v204, v[212:215]
	ds_write_b128 v204, v[216:219] offset:8448
	ds_write_b128 v204, v[220:223] offset:16896
	ds_write_b128 v204, v[224:227] offset:25344
	ds_write_b128 v204, v[234:237] offset:33792
	ds_write_b128 v204, v[238:241] offset:42240
	ds_write_b128 v204, v[242:245] offset:50688
	ds_write_b64 v204, v[228:229] offset:59136
	ds_write_b64 v204, v[250:251] offset:59144
	global_load_dwordx4 v[188:191], v[172:173], off offset:128
	v_add_co_u32_e32 v192, vcc, s77, v172
	s_nop 1
	v_addc_co_u32_e32 v193, vcc, 0, v173, vcc
	global_load_dwordx4 v[192:195], v[192:193], off offset:128
	global_load_dwordx4 v[196:199], v[176:177], off offset:128
	v_add_co_u32_e32 v246, vcc, s77, v176
	s_nop 1
	v_addc_co_u32_e32 v247, vcc, 0, v177, vcc
	global_load_dwordx4 v[246:249], v[246:247], off offset:128
	v_add_co_u32_e32 v234, vcc, 0x60000, v176
	s_nop 1
	v_addc_co_u32_e32 v235, vcc, 0, v177, vcc
	global_load_dwordx4 v[234:237], v[234:235], off offset:128
	v_add_co_u32_e32 v238, vcc, 0x90000, v176
	s_nop 1
	v_addc_co_u32_e32 v239, vcc, 0, v177, vcc
	global_load_dwordx4 v[238:241], v[238:239], off offset:128
	s_waitcnt lgkmcnt(0)
	s_barrier
; __device__ __forceinline__ float bf2f(u16 h) { return __uint_as_float(((u32)h) << 16); }
; __device__ __forceinline__ float sigmoidf_(float x) { return 1.0f / (1.0f + __expf(-x)); }
; __device__ __forceinline__ void phase_merge(const Params& p, u16* smem, volatile LAS unsigned* vb_) {
;     ...
;       for (int i = 0; i < 4; ++i)
; #pragma unroll
;         for (int j = 0; j < 4; ++j)
; #pragma unroll
;           for (int r = 0; r < 4; ++r) {
;             const float g = sigmoidf_(bf2f(smem[(wm * 64 + i * 16 + (lane >> 4) * 4 + r) * 264 + wn * 64 + j * 16 + (lane & 15)]));
;             tot[i][j][r] += g * acc[i][j][r];
;             if (r == 3) __builtin_amdgcn_sched_barrier(0);
;           }
	v_mov_b32_e32 v228, 0xbfb8aa3b
	v_mov_b32_e32 v250, 1.0
	ds_read_u16 v212, v94
	ds_read_u16 v213, v94 offset:528
	ds_read_u16 v214, v94 offset:1056
	ds_read_u16 v215, v94 offset:1584
	ds_read_u16 v216, v94 offset:32
	ds_read_u16 v217, v94 offset:560
	ds_read_u16 v218, v94 offset:1088
	ds_read_u16 v219, v94 offset:1616
	s_waitcnt lgkmcnt(0)
	ds_read_u16 v204, v94 offset:64
	ds_read_u16 v205, v94 offset:592
	ds_read_u16 v206, v94 offset:1120
	ds_read_u16 v207, v94 offset:1648
	ds_read_u16 v208, v94 offset:96
	ds_read_u16 v209, v94 offset:624
	ds_read_u16 v210, v94 offset:1152
	ds_read_u16 v211, v94 offset:1680
	v_lshlrev_b32_e32 v212, 16, v212
	v_lshlrev_b32_e32 v213, 16, v213
	v_lshlrev_b32_e32 v214, 16, v214
	v_lshlrev_b32_e32 v215, 16, v215
	v_lshlrev_b32_e32 v216, 16, v216
	v_lshlrev_b32_e32 v217, 16, v217
	v_lshlrev_b32_e32 v218, 16, v218
	v_lshlrev_b32_e32 v219, 16, v219
	v_pk_mul_f32 v[212:213], v[212:213], v[228:229] op_sel_hi:[1,0]
	v_pk_mul_f32 v[214:215], v[214:215], v[228:229] op_sel_hi:[1,0]
	v_pk_mul_f32 v[216:217], v[216:217], v[228:229] op_sel_hi:[1,0]
	v_pk_mul_f32 v[218:219], v[218:219], v[228:229] op_sel_hi:[1,0]
	v_min_f32_e32 v212, 0x42fc0000, v212
	v_min_f32_e32 v213, 0x42fc0000, v213
	v_min_f32_e32 v214, 0x42fc0000, v214
	v_min_f32_e32 v215, 0x42fc0000, v215
	v_min_f32_e32 v216, 0x42fc0000, v216
	v_min_f32_e32 v217, 0x42fc0000, v217
	v_min_f32_e32 v218, 0x42fc0000, v218
	v_min_f32_e32 v219, 0x42fc0000, v219
	v_exp_f32_e32 v212, v212
	v_exp_f32_e32 v213, v213
	v_exp_f32_e32 v214, v214
	v_exp_f32_e32 v215, v215
	v_exp_f32_e32 v216, v216
	v_exp_f32_e32 v217, v217
	v_exp_f32_e32 v218, v218
	v_exp_f32_e32 v219, v219
	v_pk_add_f32 v[212:213], v[212:213], v[250:251] op_sel_hi:[1,0]
	v_pk_add_f32 v[214:215], v[214:215], v[250:251] op_sel_hi:[1,0]
	v_pk_add_f32 v[216:217], v[216:217], v[250:251] op_sel_hi:[1,0]
	v_pk_add_f32 v[218:219], v[218:219], v[250:251] op_sel_hi:[1,0]
	v_rcp_f32_e32 v220, v212
	v_rcp_f32_e32 v221, v213
	v_rcp_f32_e32 v222, v214
	v_rcp_f32_e32 v223, v215
	v_rcp_f32_e32 v224, v216
	v_rcp_f32_e32 v225, v217
	v_rcp_f32_e32 v226, v218
	v_rcp_f32_e32 v227, v219
	v_pk_fma_f32 v[212:213], v[212:213], v[220:221], v[250:251] op_sel_hi:[1,1,0] neg_lo:[1,0,0] neg_hi:[1,0,0]
	v_pk_fma_f32 v[214:215], v[214:215], v[222:223], v[250:251] op_sel_hi:[1,1,0] neg_lo:[1,0,0] neg_hi:[1,0,0]
	v_pk_fma_f32 v[216:217], v[216:217], v[224:225], v[250:251] op_sel_hi:[1,1,0] neg_lo:[1,0,0] neg_hi:[1,0,0]
	v_pk_fma_f32 v[218:219], v[218:219], v[226:227], v[250:251] op_sel_hi:[1,1,0] neg_lo:[1,0,0] neg_hi:[1,0,0]
	v_pk_fma_f32 v[220:221], v[212:213], v[220:221], v[220:221]
	v_pk_fma_f32 v[222:223], v[214:215], v[222:223], v[222:223]
	v_pk_fma_f32 v[224:225], v[216:217], v[224:225], v[224:225]
	v_pk_fma_f32 v[226:227], v[218:219], v[226:227], v[226:227]
	v_pk_fma_f32 v[170:171], v[86:87], v[220:221], v[170:171]
	v_pk_fma_f32 v[168:169], v[88:89], v[222:223], v[168:169]
	v_pk_fma_f32 v[166:167], v[82:83], v[224:225], v[166:167]
	v_pk_fma_f32 v[164:165], v[84:85], v[226:227], v[164:165]
	s_waitcnt lgkmcnt(0)
	ds_read_u16 v212, v94 offset:8448
	ds_read_u16 v213, v94 offset:8976
	ds_read_u16 v214, v94 offset:9504
	ds_read_u16 v215, v94 offset:10032
	ds_read_u16 v216, v94 offset:8480
	ds_read_u16 v217, v94 offset:9008
	ds_read_u16 v218, v94 offset:9536
	ds_read_u16 v219, v94 offset:10064
	v_lshlrev_b32_e32 v204, 16, v204
	v_lshlrev_b32_e32 v205, 16, v205
	v_lshlrev_b32_e32 v206, 16, v206
	v_lshlrev_b32_e32 v207, 16, v207
	v_lshlrev_b32_e32 v208, 16, v208
	v_lshlrev_b32_e32 v209, 16, v209
	v_lshlrev_b32_e32 v210, 16, v210
	v_lshlrev_b32_e32 v211, 16, v211
	v_pk_mul_f32 v[204:205], v[204:205], v[228:229] op_sel_hi:[1,0]
	v_pk_mul_f32 v[206:207], v[206:207], v[228:229] op_sel_hi:[1,0]
	v_pk_mul_f32 v[208:209], v[208:209], v[228:229] op_sel_hi:[1,0]
	v_pk_mul_f32 v[210:211], v[210:211], v[228:229] op_sel_hi:[1,0]
	v_min_f32_e32 v204, 0x42fc0000, v204
	v_min_f32_e32 v205, 0x42fc0000, v205
	v_min_f32_e32 v206, 0x42fc0000, v206
	v_min_f32_e32 v207, 0x42fc0000, v207
	v_min_f32_e32 v208, 0x42fc0000, v208
	v_min_f32_e32 v209, 0x42fc0000, v209
	v_min_f32_e32 v210, 0x42fc0000, v210
	v_min_f32_e32 v211, 0x42fc0000, v211
	v_exp_f32_e32 v204, v204
	v_exp_f32_e32 v205, v205
	v_exp_f32_e32 v206, v206
	v_exp_f32_e32 v207, v207
	v_exp_f32_e32 v208, v208
	v_exp_f32_e32 v209, v209
	v_exp_f32_e32 v210, v210
	v_exp_f32_e32 v211, v211
	v_pk_add_f32 v[204:205], v[204:205], v[250:251] op_sel_hi:[1,0]
	v_pk_add_f32 v[206:207], v[206:207], v[250:251] op_sel_hi:[1,0]
	v_pk_add_f32 v[208:209], v[208:209], v[250:251] op_sel_hi:[1,0]
	v_pk_add_f32 v[210:211], v[210:211], v[250:251] op_sel_hi:[1,0]
	v_rcp_f32_e32 v220, v204
	v_rcp_f32_e32 v221, v205
	v_rcp_f32_e32 v222, v206
	v_rcp_f32_e32 v223, v207
	v_rcp_f32_e32 v224, v208
	v_rcp_f32_e32 v225, v209
	v_rcp_f32_e32 v226, v210
	v_rcp_f32_e32 v227, v211
	v_pk_fma_f32 v[204:205], v[204:205], v[220:221], v[250:251] op_sel_hi:[1,1,0] neg_lo:[1,0,0] neg_hi:[1,0,0]
	v_pk_fma_f32 v[206:207], v[206:207], v[222:223], v[250:251] op_sel_hi:[1,1,0] neg_lo:[1,0,0] neg_hi:[1,0,0]
	v_pk_fma_f32 v[208:209], v[208:209], v[224:225], v[250:251] op_sel_hi:[1,1,0] neg_lo:[1,0,0] neg_hi:[1,0,0]
	v_pk_fma_f32 v[210:211], v[210:211], v[226:227], v[250:251] op_sel_hi:[1,1,0] neg_lo:[1,0,0] neg_hi:[1,0,0]
	v_pk_fma_f32 v[220:221], v[204:205], v[220:221], v[220:221]
	v_pk_fma_f32 v[222:223], v[206:207], v[222:223], v[222:223]
	v_pk_fma_f32 v[224:225], v[208:209], v[224:225], v[224:225]
	v_pk_fma_f32 v[226:227], v[210:211], v[226:227], v[226:227]
	v_pk_fma_f32 v[162:163], v[78:79], v[220:221], v[162:163]
	v_pk_fma_f32 v[160:161], v[80:81], v[222:223], v[160:161]
	v_pk_fma_f32 v[158:159], v[74:75], v[224:225], v[158:159]
	v_pk_fma_f32 v[156:157], v[76:77], v[226:227], v[156:157]
	s_waitcnt lgkmcnt(0)
; __device__ __forceinline__ float bf2f(u16 h) { return __uint_as_float(((u32)h) << 16); }
; __device__ __forceinline__ float sigmoidf_(float x) { return 1.0f / (1.0f + __expf(-x)); }
; __device__ __forceinline__ void phase_merge(const Params& p, u16* smem, volatile LAS unsigned* vb_) {
;     ...
;       for (int i = 0; i < 4; ++i)
; #pragma unroll
;         for (int j = 0; j < 4; ++j)
; #pragma unroll
;           for (int r = 0; r < 4; ++r) {
;             const float g = sigmoidf_(bf2f(smem[(wm * 64 + i * 16 + (lane >> 4) * 4 + r) * 264 + wn * 64 + j * 16 + (lane & 15)]));
;             tot[i][j][r] += g * acc[i][j][r];
;             if (r == 3) __builtin_amdgcn_sched_barrier(0);
;           }
	ds_read_u16 v204, v94 offset:8512
	ds_read_u16 v205, v94 offset:9040
	ds_read_u16 v206, v94 offset:9568
	ds_read_u16 v207, v94 offset:10096
	ds_read_u16 v208, v94 offset:8544
	ds_read_u16 v209, v94 offset:9072
	ds_read_u16 v210, v94 offset:9600
	ds_read_u16 v211, v94 offset:10128
	v_lshlrev_b32_e32 v212, 16, v212
	v_lshlrev_b32_e32 v213, 16, v213
	v_lshlrev_b32_e32 v214, 16, v214
	v_lshlrev_b32_e32 v215, 16, v215
	v_lshlrev_b32_e32 v216, 16, v216
	v_lshlrev_b32_e32 v217, 16, v217
	v_lshlrev_b32_e32 v218, 16, v218
	v_lshlrev_b32_e32 v219, 16, v219
	v_pk_mul_f32 v[212:213], v[212:213], v[228:229] op_sel_hi:[1,0]
	v_pk_mul_f32 v[214:215], v[214:215], v[228:229] op_sel_hi:[1,0]
	v_pk_mul_f32 v[216:217], v[216:217], v[228:229] op_sel_hi:[1,0]
	v_pk_mul_f32 v[218:219], v[218:219], v[228:229] op_sel_hi:[1,0]
	v_min_f32_e32 v212, 0x42fc0000, v212
	v_min_f32_e32 v213, 0x42fc0000, v213
	v_min_f32_e32 v214, 0x42fc0000, v214
	v_min_f32_e32 v215, 0x42fc0000, v215
	v_min_f32_e32 v216, 0x42fc0000, v216
	v_min_f32_e32 v217, 0x42fc0000, v217
	v_min_f32_e32 v218, 0x42fc0000, v218
	v_min_f32_e32 v219, 0x42fc0000, v219
	v_exp_f32_e32 v212, v212
	v_exp_f32_e32 v213, v213
	v_exp_f32_e32 v214, v214
	v_exp_f32_e32 v215, v215
	v_exp_f32_e32 v216, v216
	v_exp_f32_e32 v217, v217
	v_exp_f32_e32 v218, v218
	v_exp_f32_e32 v219, v219
	v_pk_add_f32 v[212:213], v[212:213], v[250:251] op_sel_hi:[1,0]
	v_pk_add_f32 v[214:215], v[214:215], v[250:251] op_sel_hi:[1,0]
	v_pk_add_f32 v[216:217], v[216:217], v[250:251] op_sel_hi:[1,0]
	v_pk_add_f32 v[218:219], v[218:219], v[250:251] op_sel_hi:[1,0]
	v_rcp_f32_e32 v220, v212
	v_rcp_f32_e32 v221, v213
	v_rcp_f32_e32 v222, v214
	v_rcp_f32_e32 v223, v215
	v_rcp_f32_e32 v224, v216
	v_rcp_f32_e32 v225, v217
	v_rcp_f32_e32 v226, v218
	v_rcp_f32_e32 v227, v219
	v_pk_fma_f32 v[212:213], v[212:213], v[220:221], v[250:251] op_sel_hi:[1,1,0] neg_lo:[1,0,0] neg_hi:[1,0,0]
	v_pk_fma_f32 v[214:215], v[214:215], v[222:223], v[250:251] op_sel_hi:[1,1,0] neg_lo:[1,0,0] neg_hi:[1,0,0]
	v_pk_fma_f32 v[216:217], v[216:217], v[224:225], v[250:251] op_sel_hi:[1,1,0] neg_lo:[1,0,0] neg_hi:[1,0,0]
	v_pk_fma_f32 v[218:219], v[218:219], v[226:227], v[250:251] op_sel_hi:[1,1,0] neg_lo:[1,0,0] neg_hi:[1,0,0]
	v_pk_fma_f32 v[220:221], v[212:213], v[220:221], v[220:221]
	v_pk_fma_f32 v[222:223], v[214:215], v[222:223], v[222:223]
	v_pk_fma_f32 v[224:225], v[216:217], v[224:225], v[224:225]
	v_pk_fma_f32 v[226:227], v[218:219], v[226:227], v[226:227]
	v_pk_fma_f32 v[154:155], v[70:71], v[220:221], v[154:155]
	v_pk_fma_f32 v[152:153], v[72:73], v[222:223], v[152:153]
	v_pk_fma_f32 v[150:151], v[66:67], v[224:225], v[150:151]
	v_pk_fma_f32 v[148:149], v[68:69], v[226:227], v[148:149]
	s_waitcnt lgkmcnt(0)
	ds_read_u16 v212, v94 offset:16896
	ds_read_u16 v213, v94 offset:17424
	ds_read_u16 v214, v94 offset:17952
	ds_read_u16 v215, v94 offset:18480
	ds_read_u16 v216, v94 offset:16928
	ds_read_u16 v217, v94 offset:17456
	ds_read_u16 v218, v94 offset:17984
	ds_read_u16 v219, v94 offset:18512
	v_lshlrev_b32_e32 v204, 16, v204
	v_lshlrev_b32_e32 v205, 16, v205
	v_lshlrev_b32_e32 v206, 16, v206
	v_lshlrev_b32_e32 v207, 16, v207
	v_lshlrev_b32_e32 v208, 16, v208
	v_lshlrev_b32_e32 v209, 16, v209
	v_lshlrev_b32_e32 v210, 16, v210
	v_lshlrev_b32_e32 v211, 16, v211
	v_pk_mul_f32 v[204:205], v[204:205], v[228:229] op_sel_hi:[1,0]
	v_pk_mul_f32 v[206:207], v[206:207], v[228:229] op_sel_hi:[1,0]
	v_pk_mul_f32 v[208:209], v[208:209], v[228:229] op_sel_hi:[1,0]
	v_pk_mul_f32 v[210:211], v[210:211], v[228:229] op_sel_hi:[1,0]
	v_min_f32_e32 v204, 0x42fc0000, v204
	v_min_f32_e32 v205, 0x42fc0000, v205
	v_min_f32_e32 v206, 0x42fc0000, v206
	v_min_f32_e32 v207, 0x42fc0000, v207
	v_min_f32_e32 v208, 0x42fc0000, v208
	v_min_f32_e32 v209, 0x42fc0000, v209
	v_min_f32_e32 v210, 0x42fc0000, v210
	v_min_f32_e32 v211, 0x42fc0000, v211
	v_exp_f32_e32 v204, v204
	v_exp_f32_e32 v205, v205
	v_exp_f32_e32 v206, v206
	v_exp_f32_e32 v207, v207
	v_exp_f32_e32 v208, v208
	v_exp_f32_e32 v209, v209
	v_exp_f32_e32 v210, v210
	v_exp_f32_e32 v211, v211
	v_pk_add_f32 v[204:205], v[204:205], v[250:251] op_sel_hi:[1,0]
	v_pk_add_f32 v[206:207], v[206:207], v[250:251] op_sel_hi:[1,0]
	v_pk_add_f32 v[208:209], v[208:209], v[250:251] op_sel_hi:[1,0]
	v_pk_add_f32 v[210:211], v[210:211], v[250:251] op_sel_hi:[1,0]
	v_rcp_f32_e32 v220, v204
	v_rcp_f32_e32 v221, v205
	v_rcp_f32_e32 v222, v206
	v_rcp_f32_e32 v223, v207
	v_rcp_f32_e32 v224, v208
	v_rcp_f32_e32 v225, v209
	v_rcp_f32_e32 v226, v210
	v_rcp_f32_e32 v227, v211
	v_pk_fma_f32 v[204:205], v[204:205], v[220:221], v[250:251] op_sel_hi:[1,1,0] neg_lo:[1,0,0] neg_hi:[1,0,0]
	v_pk_fma_f32 v[206:207], v[206:207], v[222:223], v[250:251] op_sel_hi:[1,1,0] neg_lo:[1,0,0] neg_hi:[1,0,0]
	v_pk_fma_f32 v[208:209], v[208:209], v[224:225], v[250:251] op_sel_hi:[1,1,0] neg_lo:[1,0,0] neg_hi:[1,0,0]
	v_pk_fma_f32 v[210:211], v[210:211], v[226:227], v[250:251] op_sel_hi:[1,1,0] neg_lo:[1,0,0] neg_hi:[1,0,0]
	v_pk_fma_f32 v[220:221], v[204:205], v[220:221], v[220:221]
	v_pk_fma_f32 v[222:223], v[206:207], v[222:223], v[222:223]
	v_pk_fma_f32 v[224:225], v[208:209], v[224:225], v[224:225]
	v_pk_fma_f32 v[226:227], v[210:211], v[226:227], v[226:227]
	v_pk_fma_f32 v[146:147], v[62:63], v[220:221], v[146:147]
	v_pk_fma_f32 v[144:145], v[64:65], v[222:223], v[144:145]
	v_pk_fma_f32 v[138:139], v[58:59], v[224:225], v[138:139]
	v_pk_fma_f32 v[136:137], v[60:61], v[226:227], v[136:137]
	s_waitcnt lgkmcnt(0)
; __device__ __forceinline__ float bf2f(u16 h) { return __uint_as_float(((u32)h) << 16); }
; __device__ __forceinline__ float sigmoidf_(float x) { return 1.0f / (1.0f + __expf(-x)); }
; __device__ __forceinline__ void phase_merge(const Params& p, u16* smem, volatile LAS unsigned* vb_) {
;     ...
;       for (int i = 0; i < 4; ++i)
; #pragma unroll
;         for (int j = 0; j < 4; ++j)
; #pragma unroll
;           for (int r = 0; r < 4; ++r) {
;             const float g = sigmoidf_(bf2f(smem[(wm * 64 + i * 16 + (lane >> 4) * 4 + r) * 264 + wn * 64 + j * 16 + (lane & 15)]));
;             tot[i][j][r] += g * acc[i][j][r];
;             if (r == 3) __builtin_amdgcn_sched_barrier(0);
;           }
	ds_read_u16 v204, v94 offset:16960
	ds_read_u16 v205, v94 offset:17488
	ds_read_u16 v206, v94 offset:18016
	ds_read_u16 v207, v94 offset:18544
	ds_read_u16 v208, v94 offset:16992
	ds_read_u16 v209, v94 offset:17520
	ds_read_u16 v210, v94 offset:18048
	ds_read_u16 v211, v94 offset:18576
	v_lshlrev_b32_e32 v212, 16, v212
	v_lshlrev_b32_e32 v213, 16, v213
	v_lshlrev_b32_e32 v214, 16, v214
	v_lshlrev_b32_e32 v215, 16, v215
	v_lshlrev_b32_e32 v216, 16, v216
	v_lshlrev_b32_e32 v217, 16, v217
	v_lshlrev_b32_e32 v218, 16, v218
	v_lshlrev_b32_e32 v219, 16, v219
	v_pk_mul_f32 v[212:213], v[212:213], v[228:229] op_sel_hi:[1,0]
	v_pk_mul_f32 v[214:215], v[214:215], v[228:229] op_sel_hi:[1,0]
	v_pk_mul_f32 v[216:217], v[216:217], v[228:229] op_sel_hi:[1,0]
	v_pk_mul_f32 v[218:219], v[218:219], v[228:229] op_sel_hi:[1,0]
	v_min_f32_e32 v212, 0x42fc0000, v212
	v_min_f32_e32 v213, 0x42fc0000, v213
	v_min_f32_e32 v214, 0x42fc0000, v214
	v_min_f32_e32 v215, 0x42fc0000, v215
	v_min_f32_e32 v216, 0x42fc0000, v216
	v_min_f32_e32 v217, 0x42fc0000, v217
	v_min_f32_e32 v218, 0x42fc0000, v218
	v_min_f32_e32 v219, 0x42fc0000, v219
	v_exp_f32_e32 v212, v212
	v_exp_f32_e32 v213, v213
	v_exp_f32_e32 v214, v214
	v_exp_f32_e32 v215, v215
	v_exp_f32_e32 v216, v216
	v_exp_f32_e32 v217, v217
	v_exp_f32_e32 v218, v218
	v_exp_f32_e32 v219, v219
	v_pk_add_f32 v[212:213], v[212:213], v[250:251] op_sel_hi:[1,0]
	v_pk_add_f32 v[214:215], v[214:215], v[250:251] op_sel_hi:[1,0]
	v_pk_add_f32 v[216:217], v[216:217], v[250:251] op_sel_hi:[1,0]
	v_pk_add_f32 v[218:219], v[218:219], v[250:251] op_sel_hi:[1,0]
	v_rcp_f32_e32 v220, v212
	v_rcp_f32_e32 v221, v213
	v_rcp_f32_e32 v222, v214
	v_rcp_f32_e32 v223, v215
	v_rcp_f32_e32 v224, v216
	v_rcp_f32_e32 v225, v217
	v_rcp_f32_e32 v226, v218
	v_rcp_f32_e32 v227, v219
	v_pk_fma_f32 v[212:213], v[212:213], v[220:221], v[250:251] op_sel_hi:[1,1,0] neg_lo:[1,0,0] neg_hi:[1,0,0]
	v_pk_fma_f32 v[214:215], v[214:215], v[222:223], v[250:251] op_sel_hi:[1,1,0] neg_lo:[1,0,0] neg_hi:[1,0,0]
	v_pk_fma_f32 v[216:217], v[216:217], v[224:225], v[250:251] op_sel_hi:[1,1,0] neg_lo:[1,0,0] neg_hi:[1,0,0]
	v_pk_fma_f32 v[218:219], v[218:219], v[226:227], v[250:251] op_sel_hi:[1,1,0] neg_lo:[1,0,0] neg_hi:[1,0,0]
	v_pk_fma_f32 v[220:221], v[212:213], v[220:221], v[220:221]
	v_pk_fma_f32 v[222:223], v[214:215], v[222:223], v[222:223]
	v_pk_fma_f32 v[224:225], v[216:217], v[224:225], v[224:225]
	v_pk_fma_f32 v[226:227], v[218:219], v[226:227], v[226:227]
	v_pk_fma_f32 v[134:135], v[54:55], v[220:221], v[134:135]
	v_pk_fma_f32 v[130:131], v[56:57], v[222:223], v[130:131]
	v_pk_fma_f32 v[126:127], v[50:51], v[224:225], v[126:127]
	v_pk_fma_f32 v[124:125], v[52:53], v[226:227], v[124:125]
	s_waitcnt lgkmcnt(0)
	ds_read_u16 v212, v94 offset:25344
	ds_read_u16 v213, v94 offset:25872
	ds_read_u16 v214, v94 offset:26400
	ds_read_u16 v215, v94 offset:26928
	ds_read_u16 v216, v94 offset:25376
	ds_read_u16 v217, v94 offset:25904
	ds_read_u16 v218, v94 offset:26432
	ds_read_u16 v219, v94 offset:26960
	v_lshlrev_b32_e32 v204, 16, v204
	v_lshlrev_b32_e32 v205, 16, v205
	v_lshlrev_b32_e32 v206, 16, v206
	v_lshlrev_b32_e32 v207, 16, v207
	v_lshlrev_b32_e32 v208, 16, v208
	v_lshlrev_b32_e32 v209, 16, v209
	v_lshlrev_b32_e32 v210, 16, v210
	v_lshlrev_b32_e32 v211, 16, v211
	v_pk_mul_f32 v[204:205], v[204:205], v[228:229] op_sel_hi:[1,0]
	v_pk_mul_f32 v[206:207], v[206:207], v[228:229] op_sel_hi:[1,0]
	v_pk_mul_f32 v[208:209], v[208:209], v[228:229] op_sel_hi:[1,0]
	v_pk_mul_f32 v[210:211], v[210:211], v[228:229] op_sel_hi:[1,0]
	v_min_f32_e32 v204, 0x42fc0000, v204
	v_min_f32_e32 v205, 0x42fc0000, v205
	v_min_f32_e32 v206, 0x42fc0000, v206
	v_min_f32_e32 v207, 0x42fc0000, v207
	v_min_f32_e32 v208, 0x42fc0000, v208
	v_min_f32_e32 v209, 0x42fc0000, v209
	v_min_f32_e32 v210, 0x42fc0000, v210
	v_min_f32_e32 v211, 0x42fc0000, v211
	v_exp_f32_e32 v204, v204
	v_exp_f32_e32 v205, v205
	v_exp_f32_e32 v206, v206
	v_exp_f32_e32 v207, v207
	v_exp_f32_e32 v208, v208
	v_exp_f32_e32 v209, v209
	v_exp_f32_e32 v210, v210
	v_exp_f32_e32 v211, v211
	v_pk_add_f32 v[204:205], v[204:205], v[250:251] op_sel_hi:[1,0]
	v_pk_add_f32 v[206:207], v[206:207], v[250:251] op_sel_hi:[1,0]
	v_pk_add_f32 v[208:209], v[208:209], v[250:251] op_sel_hi:[1,0]
	v_pk_add_f32 v[210:211], v[210:211], v[250:251] op_sel_hi:[1,0]
	v_rcp_f32_e32 v220, v204
	v_rcp_f32_e32 v221, v205
	v_rcp_f32_e32 v222, v206
	v_rcp_f32_e32 v223, v207
	v_rcp_f32_e32 v224, v208
	v_rcp_f32_e32 v225, v209
	v_rcp_f32_e32 v226, v210
	v_rcp_f32_e32 v227, v211
	v_pk_fma_f32 v[204:205], v[204:205], v[220:221], v[250:251] op_sel_hi:[1,1,0] neg_lo:[1,0,0] neg_hi:[1,0,0]
	v_pk_fma_f32 v[206:207], v[206:207], v[222:223], v[250:251] op_sel_hi:[1,1,0] neg_lo:[1,0,0] neg_hi:[1,0,0]
	v_pk_fma_f32 v[208:209], v[208:209], v[224:225], v[250:251] op_sel_hi:[1,1,0] neg_lo:[1,0,0] neg_hi:[1,0,0]
	v_pk_fma_f32 v[210:211], v[210:211], v[226:227], v[250:251] op_sel_hi:[1,1,0] neg_lo:[1,0,0] neg_hi:[1,0,0]
	v_pk_fma_f32 v[220:221], v[204:205], v[220:221], v[220:221]
	v_pk_fma_f32 v[222:223], v[206:207], v[222:223], v[222:223]
	v_pk_fma_f32 v[224:225], v[208:209], v[224:225], v[224:225]
	v_pk_fma_f32 v[226:227], v[210:211], v[226:227], v[226:227]
	v_pk_fma_f32 v[122:123], v[46:47], v[220:221], v[122:123]
	v_pk_fma_f32 v[120:121], v[48:49], v[222:223], v[120:121]
	v_pk_fma_f32 v[118:119], v[42:43], v[224:225], v[118:119]
	v_pk_fma_f32 v[116:117], v[44:45], v[226:227], v[116:117]
	s_waitcnt lgkmcnt(0)
; __device__ __forceinline__ float bf2f(u16 h) { return __uint_as_float(((u32)h) << 16); }
; __device__ __forceinline__ float sigmoidf_(float x) { return 1.0f / (1.0f + __expf(-x)); }
; __device__ __forceinline__ void phase_merge(const Params& p, u16* smem, volatile LAS unsigned* vb_) {
;     ...
;     for (int n = 0; n < 3; ++n) {
;     ...
;       for (int i = 0; i < 4; ++i)
; #pragma unroll
;         for (int j = 0; j < 4; ++j)
; #pragma unroll
;           for (int r = 0; r < 4; ++r) {
;             const float g = sigmoidf_(bf2f(smem[(wm * 64 + i * 16 + (lane >> 4) * 4 + r) * 264 + wn * 64 + j * 16 + (lane & 15)]));
;             tot[i][j][r] += g * acc[i][j][r];
;             if (r == 3) __builtin_amdgcn_sched_barrier(0);
;           }
;       __syncthreads();
	ds_read_u16 v204, v94 offset:25408
	ds_read_u16 v205, v94 offset:25936
	ds_read_u16 v206, v94 offset:26464
	ds_read_u16 v207, v94 offset:26992
	ds_read_u16 v208, v94 offset:25440
	ds_read_u16 v209, v94 offset:25968
	ds_read_u16 v210, v94 offset:26496
	ds_read_u16 v211, v94 offset:27024
	v_lshlrev_b32_e32 v212, 16, v212
	v_lshlrev_b32_e32 v213, 16, v213
	v_lshlrev_b32_e32 v214, 16, v214
	v_lshlrev_b32_e32 v215, 16, v215
	v_lshlrev_b32_e32 v216, 16, v216
	v_lshlrev_b32_e32 v217, 16, v217
	v_lshlrev_b32_e32 v218, 16, v218
	v_lshlrev_b32_e32 v219, 16, v219
	v_pk_mul_f32 v[212:213], v[212:213], v[228:229] op_sel_hi:[1,0]
	v_pk_mul_f32 v[214:215], v[214:215], v[228:229] op_sel_hi:[1,0]
	v_pk_mul_f32 v[216:217], v[216:217], v[228:229] op_sel_hi:[1,0]
	v_pk_mul_f32 v[218:219], v[218:219], v[228:229] op_sel_hi:[1,0]
	v_min_f32_e32 v212, 0x42fc0000, v212
	v_min_f32_e32 v213, 0x42fc0000, v213
	v_min_f32_e32 v214, 0x42fc0000, v214
	v_min_f32_e32 v215, 0x42fc0000, v215
	v_min_f32_e32 v216, 0x42fc0000, v216
	v_min_f32_e32 v217, 0x42fc0000, v217
	v_min_f32_e32 v218, 0x42fc0000, v218
	v_min_f32_e32 v219, 0x42fc0000, v219
	v_exp_f32_e32 v212, v212
	v_exp_f32_e32 v213, v213
	v_exp_f32_e32 v214, v214
	v_exp_f32_e32 v215, v215
	v_exp_f32_e32 v216, v216
	v_exp_f32_e32 v217, v217
	v_exp_f32_e32 v218, v218
	v_exp_f32_e32 v219, v219
	v_pk_add_f32 v[212:213], v[212:213], v[250:251] op_sel_hi:[1,0]
	v_pk_add_f32 v[214:215], v[214:215], v[250:251] op_sel_hi:[1,0]
	v_pk_add_f32 v[216:217], v[216:217], v[250:251] op_sel_hi:[1,0]
	v_pk_add_f32 v[218:219], v[218:219], v[250:251] op_sel_hi:[1,0]
	v_rcp_f32_e32 v220, v212
	v_rcp_f32_e32 v221, v213
	v_rcp_f32_e32 v222, v214
	v_rcp_f32_e32 v223, v215
	v_rcp_f32_e32 v224, v216
	v_rcp_f32_e32 v225, v217
	v_rcp_f32_e32 v226, v218
	v_rcp_f32_e32 v227, v219
	v_pk_fma_f32 v[212:213], v[212:213], v[220:221], v[250:251] op_sel_hi:[1,1,0] neg_lo:[1,0,0] neg_hi:[1,0,0]
	v_pk_fma_f32 v[214:215], v[214:215], v[222:223], v[250:251] op_sel_hi:[1,1,0] neg_lo:[1,0,0] neg_hi:[1,0,0]
	v_pk_fma_f32 v[216:217], v[216:217], v[224:225], v[250:251] op_sel_hi:[1,1,0] neg_lo:[1,0,0] neg_hi:[1,0,0]
	v_pk_fma_f32 v[218:219], v[218:219], v[226:227], v[250:251] op_sel_hi:[1,1,0] neg_lo:[1,0,0] neg_hi:[1,0,0]
	v_pk_fma_f32 v[220:221], v[212:213], v[220:221], v[220:221]
	v_pk_fma_f32 v[222:223], v[214:215], v[222:223], v[222:223]
	v_pk_fma_f32 v[224:225], v[216:217], v[224:225], v[224:225]
	v_pk_fma_f32 v[226:227], v[218:219], v[226:227], v[226:227]
	v_pk_fma_f32 v[114:115], v[38:39], v[220:221], v[114:115]
	v_pk_fma_f32 v[112:113], v[40:41], v[222:223], v[112:113]
	v_pk_fma_f32 v[110:111], v[34:35], v[224:225], v[110:111]
	v_pk_fma_f32 v[108:109], v[36:37], v[226:227], v[108:109]
	s_waitcnt lgkmcnt(0)
	v_lshlrev_b32_e32 v204, 16, v204
	v_lshlrev_b32_e32 v205, 16, v205
	v_lshlrev_b32_e32 v206, 16, v206
	v_lshlrev_b32_e32 v207, 16, v207
	v_lshlrev_b32_e32 v208, 16, v208
	v_lshlrev_b32_e32 v209, 16, v209
	v_lshlrev_b32_e32 v210, 16, v210
	v_lshlrev_b32_e32 v211, 16, v211
	v_pk_mul_f32 v[204:205], v[204:205], v[228:229] op_sel_hi:[1,0]
	v_pk_mul_f32 v[206:207], v[206:207], v[228:229] op_sel_hi:[1,0]
	v_pk_mul_f32 v[208:209], v[208:209], v[228:229] op_sel_hi:[1,0]
	v_pk_mul_f32 v[210:211], v[210:211], v[228:229] op_sel_hi:[1,0]
	v_min_f32_e32 v204, 0x42fc0000, v204
	v_min_f32_e32 v205, 0x42fc0000, v205
	v_min_f32_e32 v206, 0x42fc0000, v206
	v_min_f32_e32 v207, 0x42fc0000, v207
	v_min_f32_e32 v208, 0x42fc0000, v208
	v_min_f32_e32 v209, 0x42fc0000, v209
	v_min_f32_e32 v210, 0x42fc0000, v210
	v_min_f32_e32 v211, 0x42fc0000, v211
	v_exp_f32_e32 v204, v204
	v_exp_f32_e32 v205, v205
	v_exp_f32_e32 v206, v206
	v_exp_f32_e32 v207, v207
	v_exp_f32_e32 v208, v208
	v_exp_f32_e32 v209, v209
	v_exp_f32_e32 v210, v210
	v_exp_f32_e32 v211, v211
	v_pk_add_f32 v[204:205], v[204:205], v[250:251] op_sel_hi:[1,0]
	v_pk_add_f32 v[206:207], v[206:207], v[250:251] op_sel_hi:[1,0]
	v_pk_add_f32 v[208:209], v[208:209], v[250:251] op_sel_hi:[1,0]
	v_pk_add_f32 v[210:211], v[210:211], v[250:251] op_sel_hi:[1,0]
	v_rcp_f32_e32 v220, v204
	v_rcp_f32_e32 v221, v205
	v_rcp_f32_e32 v222, v206
	v_rcp_f32_e32 v223, v207
	v_rcp_f32_e32 v224, v208
	v_rcp_f32_e32 v225, v209
	v_rcp_f32_e32 v226, v210
	v_rcp_f32_e32 v227, v211
	v_pk_fma_f32 v[204:205], v[204:205], v[220:221], v[250:251] op_sel_hi:[1,1,0] neg_lo:[1,0,0] neg_hi:[1,0,0]
	v_pk_fma_f32 v[206:207], v[206:207], v[222:223], v[250:251] op_sel_hi:[1,1,0] neg_lo:[1,0,0] neg_hi:[1,0,0]
	v_pk_fma_f32 v[208:209], v[208:209], v[224:225], v[250:251] op_sel_hi:[1,1,0] neg_lo:[1,0,0] neg_hi:[1,0,0]
	v_pk_fma_f32 v[210:211], v[210:211], v[226:227], v[250:251] op_sel_hi:[1,1,0] neg_lo:[1,0,0] neg_hi:[1,0,0]
	v_pk_fma_f32 v[220:221], v[204:205], v[220:221], v[220:221]
	v_pk_fma_f32 v[222:223], v[206:207], v[222:223], v[222:223]
	v_pk_fma_f32 v[224:225], v[208:209], v[224:225], v[224:225]
	v_pk_fma_f32 v[226:227], v[210:211], v[226:227], v[226:227]
	v_pk_fma_f32 v[106:107], v[30:31], v[220:221], v[106:107]
	v_pk_fma_f32 v[104:105], v[32:33], v[222:223], v[104:105]
	v_pk_fma_f32 v[100:101], v[26:27], v[224:225], v[100:101]
	v_pk_fma_f32 v[102:103], v[28:29], v[226:227], v[102:103]
	s_add_i32 s39, s39, 1
	v_lshl_add_u64 v[128:129], v[128:129], 0, s[18:19]
	v_lshl_add_u64 v[132:133], v[132:133], 0, s[18:19]
	s_cmp_eq_u32 s39, 3
	s_mov_b64 s[12:13], -1
	s_barrier
	s_cbranch_scc0 .LBB0_23
; __device__ __forceinline__ void phase_merge(const Params& p, u16* smem, volatile LAS unsigned* vb_) {
;     ...
; #pragma unroll
;     for (int i = 0; i < 4; ++i)
; #pragma unroll
;       for (int j = 0; j < 4; ++j)
; #pragma unroll
;         for (int r = 0; r < 4; ++r)
;           smem[(wm * 64 + i * 16 + (lane >> 4) * 4 + r) * 264 + wn * 64 + j * 16 + (lane & 15)] = f2bf(tot[i][j][r]);
;     __syncthreads();
	v_cvt_pk_bf16_f32 v0, v170, s0
	ds_write_b16 v94, v0
	v_cvt_pk_bf16_f32 v0, v171, s0
	ds_write_b16 v94, v0 offset:528
	v_cvt_pk_bf16_f32 v0, v168, s0
	ds_write_b16 v94, v0 offset:1056
	v_cvt_pk_bf16_f32 v0, v169, s0
	ds_write_b16 v94, v0 offset:1584
	v_cvt_pk_bf16_f32 v0, v166, s0
	ds_write_b16 v94, v0 offset:32
	v_cvt_pk_bf16_f32 v0, v167, s0
	ds_write_b16 v94, v0 offset:560
	v_cvt_pk_bf16_f32 v0, v164, s0
	ds_write_b16 v94, v0 offset:1088
	v_cvt_pk_bf16_f32 v0, v165, s0
	ds_write_b16 v94, v0 offset:1616
	v_cvt_pk_bf16_f32 v0, v162, s0
	ds_write_b16 v94, v0 offset:64
	v_cvt_pk_bf16_f32 v0, v163, s0
	ds_write_b16 v94, v0 offset:592
	v_cvt_pk_bf16_f32 v0, v160, s0
	ds_write_b16 v94, v0 offset:1120
	v_cvt_pk_bf16_f32 v0, v161, s0
	ds_write_b16 v94, v0 offset:1648
	v_cvt_pk_bf16_f32 v0, v158, s0
	ds_write_b16 v94, v0 offset:96
	v_cvt_pk_bf16_f32 v0, v159, s0
	ds_write_b16 v94, v0 offset:624
	v_cvt_pk_bf16_f32 v0, v156, s0
	ds_write_b16 v94, v0 offset:1152
	v_cvt_pk_bf16_f32 v0, v157, s0
	ds_write_b16 v94, v0 offset:1680
	v_cvt_pk_bf16_f32 v0, v154, s0
	ds_write_b16 v94, v0 offset:8448
	v_cvt_pk_bf16_f32 v0, v155, s0
	ds_write_b16 v94, v0 offset:8976
	v_cvt_pk_bf16_f32 v0, v152, s0
	ds_write_b16 v94, v0 offset:9504
	v_cvt_pk_bf16_f32 v0, v153, s0
	ds_write_b16 v94, v0 offset:10032
	v_cvt_pk_bf16_f32 v0, v150, s0
	ds_write_b16 v94, v0 offset:8480
	v_cvt_pk_bf16_f32 v0, v151, s0
	ds_write_b16 v94, v0 offset:9008
	v_cvt_pk_bf16_f32 v0, v148, s0
	ds_write_b16 v94, v0 offset:9536
	v_cvt_pk_bf16_f32 v0, v149, s0
	ds_write_b16 v94, v0 offset:10064
	v_cvt_pk_bf16_f32 v0, v146, s0
	ds_write_b16 v94, v0 offset:8512
	v_cvt_pk_bf16_f32 v0, v147, s0
	ds_write_b16 v94, v0 offset:9040
	v_cvt_pk_bf16_f32 v0, v144, s0
	ds_write_b16 v94, v0 offset:9568
	v_cvt_pk_bf16_f32 v0, v145, s0
	ds_write_b16 v94, v0 offset:10096
	v_cvt_pk_bf16_f32 v0, v138, s0
	ds_write_b16 v94, v0 offset:8544
	v_cvt_pk_bf16_f32 v0, v139, s0
	ds_write_b16 v94, v0 offset:9072
	v_cvt_pk_bf16_f32 v0, v136, s0
	ds_write_b16 v94, v0 offset:9600
	v_cvt_pk_bf16_f32 v0, v137, s0
	ds_write_b16 v94, v0 offset:10128
	v_cvt_pk_bf16_f32 v0, v134, s0
	ds_write_b16 v94, v0 offset:16896
	v_cvt_pk_bf16_f32 v0, v135, s0
	ds_write_b16 v94, v0 offset:17424
	v_cvt_pk_bf16_f32 v0, v130, s0
	ds_write_b16 v94, v0 offset:17952
	v_cvt_pk_bf16_f32 v0, v131, s0
	ds_write_b16 v94, v0 offset:18480
	v_cvt_pk_bf16_f32 v0, v126, s0
	ds_write_b16 v94, v0 offset:16928
	v_cvt_pk_bf16_f32 v0, v127, s0
	ds_write_b16 v94, v0 offset:17456
	v_cvt_pk_bf16_f32 v0, v124, s0
	ds_write_b16 v94, v0 offset:17984
	v_cvt_pk_bf16_f32 v0, v125, s0
	ds_write_b16 v94, v0 offset:18512
	v_cvt_pk_bf16_f32 v0, v122, s0
	ds_write_b16 v94, v0 offset:16960
	v_cvt_pk_bf16_f32 v0, v123, s0
	ds_write_b16 v94, v0 offset:17488
	v_cvt_pk_bf16_f32 v0, v120, s0
	ds_write_b16 v94, v0 offset:18016
	v_cvt_pk_bf16_f32 v0, v121, s0
	ds_write_b16 v94, v0 offset:18544
	v_cvt_pk_bf16_f32 v0, v118, s0
	ds_write_b16 v94, v0 offset:16992
	v_cvt_pk_bf16_f32 v0, v119, s0
	ds_write_b16 v94, v0 offset:17520
	v_cvt_pk_bf16_f32 v0, v116, s0
	ds_write_b16 v94, v0 offset:18048
	v_cvt_pk_bf16_f32 v0, v117, s0
	ds_write_b16 v94, v0 offset:18576
	v_cvt_pk_bf16_f32 v0, v114, s0
	ds_write_b16 v94, v0 offset:25344
	v_cvt_pk_bf16_f32 v0, v115, s0
	ds_write_b16 v94, v0 offset:25872
	v_cvt_pk_bf16_f32 v0, v112, s0
	ds_write_b16 v94, v0 offset:26400
	v_cvt_pk_bf16_f32 v0, v113, s0
	ds_write_b16 v94, v0 offset:26928
	v_cvt_pk_bf16_f32 v0, v110, s0
	ds_write_b16 v94, v0 offset:25376
	v_cvt_pk_bf16_f32 v0, v111, s0
	ds_write_b16 v94, v0 offset:25904
	v_cvt_pk_bf16_f32 v0, v108, s0
	ds_write_b16 v94, v0 offset:26432
	v_cvt_pk_bf16_f32 v0, v109, s0
	ds_write_b16 v94, v0 offset:26960
	v_cvt_pk_bf16_f32 v0, v106, s0
	ds_write_b16 v94, v0 offset:25408
	v_cvt_pk_bf16_f32 v0, v107, s0
	ds_write_b16 v94, v0 offset:25936
	v_cvt_pk_bf16_f32 v0, v104, s0
	ds_write_b16 v94, v0 offset:26464
	v_cvt_pk_bf16_f32 v0, v105, s0
	ds_write_b16 v94, v0 offset:26992
	v_cvt_pk_bf16_f32 v0, v100, s0
	ds_write_b16 v94, v0 offset:25440
	v_cvt_pk_bf16_f32 v0, v101, s0
	ds_write_b16 v94, v0 offset:25968
	v_cvt_pk_bf16_f32 v0, v102, s0
	ds_write_b16 v94, v0 offset:26496
	v_cvt_pk_bf16_f32 v0, v103, s0
	v_mov_b32_e32 v38, v175
	v_readlane_b32 s12, v252, 38
	ds_write_b16 v94, v0 offset:27024
	s_waitcnt lgkmcnt(0)
	s_barrier
; #define RTID opaque_tid()
; __device__ __forceinline__ void phase_merge(const Params& p, u16* smem, volatile LAS unsigned* vb_) {
;     ...
;     const int tid3 = RTID;
; #pragma unroll
;     for (int k = 0; k < 8; ++k) {
;       const int c = tid3 + 512 * k;
;       const int row = c >> 5, ch = c & 31;
;       *(uint4*)(outp + (size_t)(mt * 128 + row) * 1024 + nt * 256 + ch * 8) = *(const uint4*)(smem + row * 264 + ch * 8);
;     }
;     __syncthreads();
;   }
	v_readlane_b32 s13, v252, 39
	v_lshlrev_b32_e32 v0, 4, v38
	s_add_u32 s12, s12, s42
	v_and_b32_e32 v0, 0x1f0, v0
	s_addc_u32 s13, s13, s43
	v_ashrrev_i32_e32 v28, 5, v38
	v_lshl_add_u64 v[34:35], s[12:13], 0, v[0:1]
	v_mad_u64_u32 v[26:27], s[12:13], v28, s2, v[0:1]
	v_add_u32_e32 v28, s22, v28
	v_ashrrev_i32_e32 v29, 31, v28
	v_lshlrev_b64 v[28:29], 11, v[28:29]
	v_lshl_add_u64 v[36:37], v[34:35], 0, v[28:29]
	ds_read_b128 v[26:29], v26
	v_add_u32_e32 v30, 0x200, v38
	v_ashrrev_i32_e32 v39, 5, v30
	v_mad_u64_u32 v[30:31], s[12:13], v39, s2, v[0:1]
	ds_read_b128 v[30:33], v30
	s_waitcnt lgkmcnt(1)
	global_store_dwordx4 v[36:37], v[26:29], off
	s_add_i32 s10, s10, s70
	s_and_b64 vcc, exec, s[0:1]
	v_add_u32_e32 v26, s22, v39
	v_ashrrev_i32_e32 v27, 31, v26
	v_lshlrev_b64 v[26:27], 11, v[26:27]
	v_lshl_add_u64 v[26:27], v[34:35], 0, v[26:27]
	s_waitcnt lgkmcnt(0)
	global_store_dwordx4 v[26:27], v[30:33], off
	v_add_u32_e32 v26, 0x400, v38
	v_ashrrev_i32_e32 v28, 5, v26
	v_mad_u64_u32 v[26:27], s[12:13], v28, s2, v[0:1]
	v_add_u32_e32 v28, s22, v28
	v_ashrrev_i32_e32 v29, 31, v28
	v_lshlrev_b64 v[28:29], 11, v[28:29]
	v_lshl_add_u64 v[36:37], v[34:35], 0, v[28:29]
	ds_read_b128 v[26:29], v26
	v_add_u32_e32 v30, 0x600, v38
	v_ashrrev_i32_e32 v39, 5, v30
	v_mad_u64_u32 v[30:31], s[12:13], v39, s2, v[0:1]
	ds_read_b128 v[30:33], v30
	s_waitcnt lgkmcnt(1)
	global_store_dwordx4 v[36:37], v[26:29], off
	s_nop 1
	v_add_u32_e32 v26, s22, v39
	v_ashrrev_i32_e32 v27, 31, v26
	v_lshlrev_b64 v[26:27], 11, v[26:27]
	v_lshl_add_u64 v[26:27], v[34:35], 0, v[26:27]
	s_waitcnt lgkmcnt(0)
	global_store_dwordx4 v[26:27], v[30:33], off
	v_add_u32_e32 v26, 0x800, v38
	v_ashrrev_i32_e32 v28, 5, v26
	v_mad_u64_u32 v[26:27], s[12:13], v28, s2, v[0:1]
	v_add_u32_e32 v28, s22, v28
	v_ashrrev_i32_e32 v29, 31, v28
	v_lshlrev_b64 v[28:29], 11, v[28:29]
	v_lshl_add_u64 v[36:37], v[34:35], 0, v[28:29]
	ds_read_b128 v[26:29], v26
	v_add_u32_e32 v30, 0xa00, v38
	v_ashrrev_i32_e32 v39, 5, v30
	v_mad_u64_u32 v[30:31], s[12:13], v39, s2, v[0:1]
	ds_read_b128 v[30:33], v30
	s_waitcnt lgkmcnt(1)
	global_store_dwordx4 v[36:37], v[26:29], off
	s_nop 1
	v_add_u32_e32 v26, s22, v39
	v_ashrrev_i32_e32 v27, 31, v26
	v_lshlrev_b64 v[26:27], 11, v[26:27]
	v_lshl_add_u64 v[26:27], v[34:35], 0, v[26:27]
	s_waitcnt lgkmcnt(0)
	global_store_dwordx4 v[26:27], v[30:33], off
	v_add_u32_e32 v26, 0xc00, v38
	v_ashrrev_i32_e32 v28, 5, v26
	v_mad_u64_u32 v[26:27], s[12:13], v28, s2, v[0:1]
	v_add_u32_e32 v28, s22, v28
	v_ashrrev_i32_e32 v29, 31, v28
	v_lshlrev_b64 v[28:29], 11, v[28:29]
	v_lshl_add_u64 v[36:37], v[34:35], 0, v[28:29]
	ds_read_b128 v[26:29], v26
	v_add_u32_e32 v30, 0xe00, v38
	v_ashrrev_i32_e32 v38, 5, v30
	v_mad_u64_u32 v[30:31], s[12:13], v38, s2, v[0:1]
	ds_read_b128 v[30:33], v30
	s_waitcnt lgkmcnt(1)
	global_store_dwordx4 v[36:37], v[26:29], off
	v_readlane_b32 s12, v254, 30
	s_add_i32 s21, s21, s12
	v_add_u32_e32 v26, s22, v38
	v_ashrrev_i32_e32 v27, 31, v26
	v_lshlrev_b64 v[26:27], 11, v[26:27]
	v_lshl_add_u64 v[26:27], v[34:35], 0, v[26:27]
	s_mov_b64 s[12:13], -1
	s_waitcnt lgkmcnt(0)
	global_store_dwordx4 v[26:27], v[30:33], off
	s_barrier
	s_cbranch_vccz .LBB0_22
